# SEL block head: selection bit tested on a scalar-selected dword (4 VALU instead of 10)
# speedup vs baseline: 1.0055x; 1.0026x over previous
; template <bool SEL> ...
;     ...
;             const int j = jhi - it, slot = it & 3;
;             bool selq[2] = {true, true}; bool any[2] = {true, true};
;             if (SEL) {
; #pragma unroll
;                 for (int cg_ = 0; cg_ < 2; ++cg_) {
;                     const unsigned long long wsel = j < 64 ? sw[cg_][0] : sw[cg_][1];
;                     selq[cg_] = ((wsel >> (j & 63)) & 1ull) != 0ull; any[cg_] = __any(selq[cg_]) != 0;
;                 }
;             }
;             if (any[0] || any[1]) {
;                 const unsigned char* Ks = lds + OFF_RING + slot * SLOTB; const unsigned char* Vs = Ks + 8192;
;                 bf16x8 kf[4][2]; load_kfrags(kf, Ks, r, fq);
;                 const bool edge = (j >= T - 2) || (wl == 512 && j == T - 8);
;                 if (edge) {
;                     if (any[0] && any[1]) step_edge<3>(kf, q, tq, j * 64, fq, H, btab, wl, selq, m, l, o, Vs, r);
.LBB0_2482:
	s_waitcnt lgkmcnt(2)
	s_and_b32 s7, s48, 31
	s_lshl_b32 s7, 1, s7
	s_lshr_b32 s6, s48, 5
	s_cmp_lt_u32 s6, 2
	s_cbranch_scc0 .Lselm_hi
	s_cmp_eq_u32 s6, 0
	s_cbranch_scc0 .Lselm_1
	v_and_b32_e32 v60, s7, v32
	v_and_b32_e32 v61, s7, v36
	s_branch .Lselm_t
.Lselm_1:
	v_and_b32_e32 v60, s7, v33
	v_and_b32_e32 v61, s7, v37
	s_branch .Lselm_t
.Lselm_hi:
	s_cmp_eq_u32 s6, 2
	s_cbranch_scc0 .Lselm_3
	v_and_b32_e32 v60, s7, v34
	v_and_b32_e32 v61, s7, v38
	s_branch .Lselm_t
.Lselm_3:
	v_and_b32_e32 v60, s7, v35
	v_and_b32_e32 v61, s7, v39
.Lselm_t:
	v_cmp_ne_u32_e64 s[10:11], 0, v60
	v_cmp_ne_u32_e64 s[8:9], 0, v61
	s_or_b64 s[6:7], s[10:11], s[8:9]
	s_cbranch_scc0 .LBB0_2481
	s_and_b32 s6, s49, 0xc000
	v_add_u32_e32 v60, s6, v140
	v_add_u32_e32 v143, v60, v136
	v_add_u32_e32 v142, v60, v137
	ds_read_b128 v[88:91], v143
	ds_read_b128 v[80:83], v143 offset:512
	ds_read_b128 v[84:87], v142
	ds_read_b128 v[76:79], v142 offset:512
	ds_read_b128 v[72:75], v143 offset:4096
	ds_read_b128 v[60:63], v143 offset:4608
	s_waitcnt lgkmcnt(7)
	ds_read_b128 v[68:71], v142 offset:4096
	s_waitcnt lgkmcnt(7)
	ds_read_b128 v[64:67], v142 offset:4608
	s_cmp_lt_i32 s48, s93
	s_cbranch_scc1 .Lsel_int
	s_branch .Lsel_edge
	s_and_b64 vcc, exec, s[38:39]
	s_cbranch_vccz .LBB0_2557
	s_and_b64 vcc, exec, s[36:37]
	s_cbranch_vccz .LBB0_2521
	s_waitcnt lgkmcnt(7)
	v_mfma_f32_16x16x32_bf16 v[92:95], v[88:91], v[10:13], 0
	v_add_u32_e32 v119, s4, v141
	v_add_u32_e32 v110, 4, v119
	v_cmp_gt_u32_e32 vcc, 2.0, v110
	s_waitcnt lgkmcnt(5)
	v_mfma_f32_16x16x32_bf16 v[104:107], v[84:87], v[14:17], v[92:95]
	v_mov_b32_e32 v108, 0xf149f2ca
	v_mov_b32_e32 v109, 0xf149f2ca
	v_mfma_f32_16x16x32_bf16 v[92:95], v[80:83], v[10:13], 0
	s_waitcnt lgkmcnt(4)
	v_mfma_f32_16x16x32_bf16 v[100:103], v[76:79], v[14:17], v[92:95]
	s_waitcnt lgkmcnt(3)
	v_mfma_f32_16x16x32_bf16 v[92:95], v[72:75], v[10:13], 0
	s_waitcnt lgkmcnt(1)
	v_mfma_f32_16x16x32_bf16 v[96:99], v[68:71], v[14:17], v[92:95]
	v_mfma_f32_16x16x32_bf16 v[92:95], v[60:63], v[10:13], 0
	s_waitcnt lgkmcnt(0)
	v_mfma_f32_16x16x32_bf16 v[92:95], v[64:67], v[14:17], v[92:95]
	s_and_saveexec_b64 s[12:13], vcc
	s_cbranch_execz .LBB0_2488
	v_min_u32_e32 v109, 0x80, v110
	v_lshl_add_u32 v109, v109, 6, v177
	ds_read_b32 v109, v109
	s_waitcnt lgkmcnt(0)
	v_add_f32_e32 v109, v104, v109
